# HL hyena conv restructured: b outer, 20 (a,ng) MFMAs per b sharing 8 Toeplitz A-fragments + 5 z-fragments (halves LDS reads, in-place alignbyte)
# baseline (speedup 1.0000x reference)
.LBB0_793:
	s_or_b64 exec, exec, s[88:89]
	v_add_u32_e32 v42, v77, v66
	v_ashrrev_i32_e32 v43, 31, v42
	v_lshl_add_u64 v[42:43], v[42:43], 2, s[34:35]
	v_ashrrev_i32_e32 v67, 31, v66
	global_load_dword v86, v[42:43], off
	v_lshl_add_u64 v[42:43], v[66:67], 0, s[74:75]
	v_lshl_add_u64 v[68:69], v[42:43], 2, s[26:27]
	global_load_dword v64, v[68:69], off offset:2048
	v_add_u32_e32 v89, s22, v1
	s_movk_i32 s22, 0xc00
	v_mul_lo_u32 v67, v89, s22
	v_add_u32_e32 v90, s17, v67
	v_lshlrev_b32_e32 v42, 1, v79
	v_lshlrev_b32_e32 v43, 1, v78
	v_mov_b32_e32 v46, 0
	s_xor_b64 s[88:89], s[90:91], -1
	s_xor_b64 s[90:91], s[92:93], -1
	v_add3_u32 v91, v90, v42, v43
	s_movk_i32 s22, 0xfee0
	v_mov_b32_e32 v47, v46
	v_mov_b32_e32 v48, v46
	v_mov_b32_e32 v49, v46
	v_mov_b32_e32 v42, v46
	v_mov_b32_e32 v43, v46
	v_mov_b32_e32 v44, v46
	v_mov_b32_e32 v45, v46
	v_mov_b32_e32 v54, v46
	v_mov_b32_e32 v55, v46
	v_mov_b32_e32 v56, v46
	v_mov_b32_e32 v57, v46
	v_mov_b32_e32 v50, v46
	v_mov_b32_e32 v51, v46
	v_mov_b32_e32 v52, v46
	v_mov_b32_e32 v53, v46
	v_add_lshl_u32 v158, v84, s22, 1
	v_and_b32_e32 v158, -4, v158
	v_add_u32_e32 v158, v65, v158
	v_add_u32_e32 v158, 0xa000, v158
	v_add_u32_e32 v154, 0x260, v158
	v_add_u32_e32 v155, 0x660, v158
	v_add_u32_e32 v156, 0xa60, v158
	v_add_u32_e32 v157, 0xe60, v158
	s_mov_b32 s22, 0
	ds_read2_b32 v[204:205], v157 offset0:128 offset1:129
	ds_read2_b32 v[206:207], v157 offset0:130 offset1:131
	ds_read_b32 v208, v157 offset:528
	ds_read_b128 v[146:149], v91 offset:2048
	ds_read2_b32 v[210:211], v157 offset1:1
	ds_read2_b32 v[212:213], v157 offset0:2 offset1:3
	ds_read_b32 v214, v157 offset:16
	ds_read_b128 v[142:145], v91 offset:1536
	ds_read2_b32 v[216:217], v156 offset0:128 offset1:129
	ds_read2_b32 v[218:219], v156 offset0:130 offset1:131
	ds_read_b32 v220, v156 offset:528
	ds_read_b128 v[138:141], v91 offset:1024
	ds_read2_b32 v[222:223], v156 offset1:1
	ds_read2_b32 v[224:225], v156 offset0:2 offset1:3
	ds_read_b32 v226, v156 offset:16
	ds_read_b128 v[244:247], v91 offset:512
	ds_read2_b32 v[228:229], v155 offset0:128 offset1:129
	ds_read2_b32 v[230:231], v155 offset0:130 offset1:131
	ds_read_b32 v232, v155 offset:528
	ds_read_b128 v[240:243], v91
	ds_read2_b32 v[234:235], v155 offset1:1
	ds_read2_b32 v[236:237], v155 offset0:2 offset1:3
	ds_read_b32 v238, v155 offset:16
	ds_read2_b32 v[126:127], v154 offset0:128 offset1:129
	ds_read2_b32 v[128:129], v154 offset0:130 offset1:131
	ds_read_b32 v130, v154 offset:528
	ds_read2_b32 v[132:133], v154 offset1:1
	ds_read2_b32 v[134:135], v154 offset0:2 offset1:3
	ds_read_b32 v136, v154 offset:16
.Lhl_cv2_a:
	s_waitcnt lgkmcnt(15)
	v_alignbyte_b32 v204, v205, v204, v80
	v_alignbyte_b32 v205, v206, v205, v80
	v_alignbyte_b32 v206, v207, v206, v80
	v_alignbyte_b32 v207, v208, v207, v80
	s_nop 0
	s_nop 0
	v_mfma_f32_16x16x32_bf16 v[50:53], v[204:207], v[146:149], v[50:53]
	ds_read2_b32 v[204:205], v157 offset0:144 offset1:145
	ds_read2_b32 v[206:207], v157 offset0:146 offset1:147
	ds_read_b32 v208, v157 offset:592
	s_waitcnt lgkmcnt(15)
	v_alignbyte_b32 v210, v211, v210, v80
	v_alignbyte_b32 v211, v212, v211, v80
	v_alignbyte_b32 v212, v213, v212, v80
	v_alignbyte_b32 v213, v214, v213, v80
	s_nop 0
	s_nop 0
	v_mfma_f32_16x16x32_bf16 v[54:57], v[210:213], v[146:149], v[54:57]
	v_mfma_f32_16x16x32_bf16 v[50:53], v[210:213], v[142:145], v[50:53]
	ds_read2_b32 v[210:211], v157 offset0:16 offset1:17
	ds_read2_b32 v[212:213], v157 offset0:18 offset1:19
	ds_read_b32 v214, v157 offset:80
	s_waitcnt lgkmcnt(14)
	v_alignbyte_b32 v216, v217, v216, v80
	v_alignbyte_b32 v217, v218, v217, v80
	v_alignbyte_b32 v218, v219, v218, v80
	v_alignbyte_b32 v219, v220, v219, v80
	s_nop 0
	s_nop 0
	v_mfma_f32_16x16x32_bf16 v[42:45], v[216:219], v[146:149], v[42:45]
	v_mfma_f32_16x16x32_bf16 v[54:57], v[216:219], v[142:145], v[54:57]
	v_mfma_f32_16x16x32_bf16 v[50:53], v[216:219], v[138:141], v[50:53]
	ds_read2_b32 v[216:217], v156 offset0:144 offset1:145
	ds_read2_b32 v[218:219], v156 offset0:146 offset1:147
	ds_read_b32 v220, v156 offset:592
	s_waitcnt lgkmcnt(13)
	v_alignbyte_b32 v222, v223, v222, v80
	v_alignbyte_b32 v223, v224, v223, v80
	v_alignbyte_b32 v224, v225, v224, v80
	v_alignbyte_b32 v225, v226, v225, v80
	s_nop 0
	s_nop 0
	v_mfma_f32_16x16x32_bf16 v[46:49], v[222:225], v[146:149], v[46:49]
	v_mfma_f32_16x16x32_bf16 v[42:45], v[222:225], v[142:145], v[42:45]
	v_mfma_f32_16x16x32_bf16 v[54:57], v[222:225], v[138:141], v[54:57]
	v_mfma_f32_16x16x32_bf16 v[50:53], v[222:225], v[244:247], v[50:53]
	ds_read2_b32 v[222:223], v156 offset0:16 offset1:17
	ds_read2_b32 v[224:225], v156 offset0:18 offset1:19
	ds_read_b32 v226, v156 offset:80
	ds_read_b128 v[146:149], v91 offset:2112
	s_waitcnt lgkmcnt(13)
	v_alignbyte_b32 v228, v229, v228, v80
	v_alignbyte_b32 v229, v230, v229, v80
	v_alignbyte_b32 v230, v231, v230, v80
	v_alignbyte_b32 v231, v232, v231, v80
	s_nop 0
	s_nop 0
	v_mfma_f32_16x16x32_bf16 v[46:49], v[228:231], v[142:145], v[46:49]
	v_mfma_f32_16x16x32_bf16 v[42:45], v[228:231], v[138:141], v[42:45]
	v_mfma_f32_16x16x32_bf16 v[54:57], v[228:231], v[244:247], v[54:57]
	v_mfma_f32_16x16x32_bf16 v[50:53], v[228:231], v[240:243], v[50:53]
	ds_read2_b32 v[228:229], v155 offset0:144 offset1:145
	ds_read2_b32 v[230:231], v155 offset0:146 offset1:147
	ds_read_b32 v232, v155 offset:592
	ds_read_b128 v[142:145], v91 offset:1600
	s_waitcnt lgkmcnt(15)
	v_alignbyte_b32 v234, v235, v234, v80
	v_alignbyte_b32 v235, v236, v235, v80
	v_alignbyte_b32 v236, v237, v236, v80
	v_alignbyte_b32 v237, v238, v237, v80
	s_nop 0
	s_nop 0
	v_mfma_f32_16x16x32_bf16 v[46:49], v[234:237], v[138:141], v[46:49]
	v_mfma_f32_16x16x32_bf16 v[42:45], v[234:237], v[244:247], v[42:45]
	v_mfma_f32_16x16x32_bf16 v[54:57], v[234:237], v[240:243], v[54:57]
	ds_read2_b32 v[234:235], v155 offset0:16 offset1:17
	ds_read2_b32 v[236:237], v155 offset0:18 offset1:19
	ds_read_b32 v238, v155 offset:80
	ds_read_b128 v[138:141], v91 offset:1088
	s_waitcnt lgkmcnt(15)
	v_alignbyte_b32 v126, v127, v126, v80
	v_alignbyte_b32 v127, v128, v127, v80
	v_alignbyte_b32 v128, v129, v128, v80
	v_alignbyte_b32 v129, v130, v129, v80
	s_nop 0
	s_nop 0
	v_mfma_f32_16x16x32_bf16 v[46:49], v[126:129], v[244:247], v[46:49]
	v_mfma_f32_16x16x32_bf16 v[42:45], v[126:129], v[240:243], v[42:45]
	ds_read2_b32 v[126:127], v154 offset0:144 offset1:145
	ds_read2_b32 v[128:129], v154 offset0:146 offset1:147
	ds_read_b32 v130, v154 offset:592
	ds_read_b128 v[244:247], v91 offset:576
	s_waitcnt lgkmcnt(15)
	v_alignbyte_b32 v132, v133, v132, v80
	v_alignbyte_b32 v133, v134, v133, v80
	v_alignbyte_b32 v134, v135, v134, v80
	v_alignbyte_b32 v135, v136, v135, v80
	s_nop 0
	s_nop 0
	v_mfma_f32_16x16x32_bf16 v[46:49], v[132:135], v[240:243], v[46:49]
	ds_read2_b32 v[132:133], v154 offset0:16 offset1:17
	ds_read2_b32 v[134:135], v154 offset0:18 offset1:19
	ds_read_b32 v136, v154 offset:80
	ds_read_b128 v[240:243], v91 offset:64
	v_add_u32_e32 v91, 64, v91
	v_add_u32_e32 v154, 64, v154
	v_add_u32_e32 v155, 64, v155
	v_add_u32_e32 v156, 64, v156
	v_add_u32_e32 v157, 64, v157
	s_add_i32 s22, s22, 1
	s_cmp_lt_i32 s22, 8
	s_cbranch_scc1 .Lhl_cv2_a
	s_waitcnt lgkmcnt(0)
	v_add_f32_e32 v58, v87, v88
	v_div_scale_f32 v59, s[22:23], v58, v58, 1.0
	v_rcp_f32_e32 v60, v59
	s_nop 0
	v_fma_f32 v61, -v59, v60, 1.0
	v_fmac_f32_e32 v60, v61, v60
	v_div_scale_f32 v61, vcc, 1.0, v58, 1.0
	v_mul_f32_e32 v87, v61, v60
	v_fma_f32 v88, -v59, v87, v61
	v_fmac_f32_e32 v87, v88, v60
	v_fma_f32 v59, -v59, v87, v61
	v_div_fmas_f32 v59, v59, v60, v87
	v_div_fixup_f32 v58, v59, v58, 1.0
	v_lshl_add_u32 v59, v81, 1, v90
	ds_read2st64_b64 v[90:93], v59 offset0:1 offset1:2
	v_lshl_add_u32 v87, v89, 11, v82
	ds_read_b64 v[60:61], v87 offset:24576
	s_waitcnt lgkmcnt(1)
	v_and_b32_e32 v127, 0xffff0000, v90
	v_lshlrev_b32_e32 v126, 16, v90
	v_pk_mul_f32 v[126:127], v[100:101], v[126:127] op_sel_hi:[0,1]
	s_waitcnt lgkmcnt(0)
	v_and_b32_e32 v89, 0xffff0000, v60
	v_lshlrev_b32_e32 v88, 16, v60
	v_pk_fma_f32 v[50:51], v[58:59], v[50:51], v[126:127] op_sel_hi:[0,1,1]
	v_pk_mul_f32 v[50:51], v[50:51], v[88:89]
	v_and_b32_e32 v89, 0xffff0000, v61
	v_lshlrev_b32_e32 v88, 16, v61
	v_and_b32_e32 v61, 0xffff0000, v91
	v_lshlrev_b32_e32 v60, 16, v91
	v_pk_mul_f32 v[60:61], v[100:101], v[60:61] op_sel_hi:[0,1]
	v_pk_fma_f32 v[52:53], v[58:59], v[52:53], v[60:61] op_sel_hi:[0,1,1]
	v_pk_mul_f32 v[52:53], v[52:53], v[88:89]
	v_bfe_u32 v88, v51, 16, 1
	v_bfe_u32 v89, v50, 16, 1
	v_add3_u32 v50, v50, v89, s94
	v_add3_u32 v88, v51, v88, s94
	v_cvt_pk_bf16_f32 v52, v52, v53
	v_mov_b32_e32 v51, v52
	v_perm_b32 v50, v88, v50, s95
	ds_write_b64 v59, v[50:51] offset:512
	ds_read_b64 v[50:51], v87 offset:25088
	v_and_b32_e32 v61, 0xffff0000, v92
	v_lshlrev_b32_e32 v60, 16, v92
	v_pk_mul_f32 v[60:61], v[100:101], v[60:61] op_sel_hi:[0,1]
	v_pk_fma_f32 v[54:55], v[58:59], v[54:55], v[60:61] op_sel_hi:[0,1,1]
	s_waitcnt lgkmcnt(0)
	v_and_b32_e32 v53, 0xffff0000, v50
	v_lshlrev_b32_e32 v52, 16, v50
	v_pk_mul_f32 v[52:53], v[54:55], v[52:53]
	v_and_b32_e32 v55, 0xffff0000, v51
	v_lshlrev_b32_e32 v54, 16, v51
	v_and_b32_e32 v51, 0xffff0000, v93
	v_lshlrev_b32_e32 v50, 16, v93
	v_pk_mul_f32 v[50:51], v[100:101], v[50:51] op_sel_hi:[0,1]
	v_pk_fma_f32 v[50:51], v[58:59], v[56:57], v[50:51] op_sel_hi:[0,1,1]
	v_pk_mul_f32 v[50:51], v[50:51], v[54:55]
	v_cvt_pk_bf16_f32 v52, v52, v53
	v_cvt_pk_bf16_f32 v50, v50, v51
	v_mov_b32_e32 v51, v50
	v_mov_b32_e32 v50, v52
	ds_write_b64 v59, v[50:51] offset:1024
	ds_read2st64_b64 v[50:53], v59 offset0:3 offset1:4
	ds_read_b64 v[54:55], v87 offset:25600
	s_waitcnt lgkmcnt(1)
	v_and_b32_e32 v61, 0xffff0000, v50
	v_lshlrev_b32_e32 v60, 16, v50
	v_pk_mul_f32 v[60:61], v[100:101], v[60:61] op_sel_hi:[0,1]
	s_waitcnt lgkmcnt(0)
	v_and_b32_e32 v57, 0xffff0000, v54
	v_lshlrev_b32_e32 v56, 16, v54
	v_pk_fma_f32 v[42:43], v[58:59], v[42:43], v[60:61] op_sel_hi:[0,1,1]
	v_pk_mul_f32 v[42:43], v[42:43], v[56:57]
	v_and_b32_e32 v57, 0xffff0000, v55
	v_lshlrev_b32_e32 v56, 16, v55
	v_and_b32_e32 v55, 0xffff0000, v51
	v_lshlrev_b32_e32 v54, 16, v51
	v_pk_mul_f32 v[50:51], v[100:101], v[54:55] op_sel_hi:[0,1]
	v_pk_fma_f32 v[44:45], v[58:59], v[44:45], v[50:51] op_sel_hi:[0,1,1]
	v_pk_mul_f32 v[44:45], v[44:45], v[56:57]
	v_bfe_u32 v54, v43, 16, 1
	v_bfe_u32 v55, v42, 16, 1
	v_add3_u32 v42, v42, v55, s94
	v_add3_u32 v54, v43, v54, s94
	v_cvt_pk_bf16_f32 v44, v44, v45
	v_mov_b32_e32 v43, v44
	v_perm_b32 v42, v54, v42, s95
	ds_write_b64 v59, v[42:43] offset:1536
	ds_read_b64 v[42:43], v87 offset:26112
	v_and_b32_e32 v51, 0xffff0000, v52
	v_lshlrev_b32_e32 v50, 16, v52
	v_pk_mul_f32 v[50:51], v[100:101], v[50:51] op_sel_hi:[0,1]
	v_pk_fma_f32 v[46:47], v[58:59], v[46:47], v[50:51] op_sel_hi:[0,1,1]
	s_waitcnt lgkmcnt(0)
	v_and_b32_e32 v45, 0xffff0000, v42
	v_lshlrev_b32_e32 v44, 16, v42
	v_pk_mul_f32 v[44:45], v[46:47], v[44:45]
	v_and_b32_e32 v47, 0xffff0000, v43
	v_lshlrev_b32_e32 v46, 16, v43
	v_and_b32_e32 v43, 0xffff0000, v53
	v_lshlrev_b32_e32 v42, 16, v53
	v_pk_mul_f32 v[42:43], v[100:101], v[42:43] op_sel_hi:[0,1]
	v_pk_fma_f32 v[42:43], v[58:59], v[48:49], v[42:43] op_sel_hi:[0,1,1]
	v_pk_mul_f32 v[42:43], v[42:43], v[46:47]
	v_cvt_pk_bf16_f32 v44, v44, v45
	v_cvt_pk_bf16_f32 v42, v42, v43
	v_mov_b32_e32 v43, v42
	v_mov_b32_e32 v42, v44
	ds_write_b64 v59, v[42:43] offset:2048
	s_waitcnt vmcnt(5)
	ds_write_b128 v70, v[26:29] offset:40992
	s_waitcnt vmcnt(4)
	ds_write_b128 v70, v[30:33] offset:42016
	s_waitcnt vmcnt(3)
	ds_write_b128 v70, v[34:37] offset:43040
	s_waitcnt vmcnt(2)
	ds_write_b128 v70, v[38:41] offset:44064
	s_and_saveexec_b64 s[92:93], s[42:43]
	ds_write_b128 v70, v[22:25] offset:45088
	s_or_b64 exec, exec, s[92:93]
	s_waitcnt vmcnt(1)
	ds_bpermute_b32 v26, v71, v86
	s_andn2_b64 vcc, exec, s[90:91]
	s_waitcnt lgkmcnt(0)
	v_add_f32_e32 v26, v86, v26
	ds_bpermute_b32 v27, v72, v26
	s_waitcnt lgkmcnt(0)
	v_add_f32_e32 v26, v26, v27
	ds_bpermute_b32 v27, v73, v26
	s_waitcnt lgkmcnt(0)
	v_add_f32_e32 v26, v26, v27
	ds_bpermute_b32 v27, v74, v26
	s_waitcnt lgkmcnt(0)
	v_add_f32_e32 v26, v26, v27
	ds_bpermute_b32 v27, v75, v26
	s_waitcnt lgkmcnt(0)
	v_add_f32_e32 v46, v26, v27
	ds_bpermute_b32 v47, v76, v46
	s_cbranch_vccnz .LBB0_801
	v_add_u32_e32 v28, 4, v66
	v_add_u32_e32 v2, s74, v28
	v_mad_i64_i32 v[26:27], s[22:23], v2, s10, v[62:63]
	global_load_dwordx4 v[2:5], v[26:27], off
	global_load_dwordx4 v[6:9], v[26:27], off offset:1024
	global_load_dwordx4 v[10:13], v[26:27], off offset:2048
	global_load_dwordx4 v[14:17], v[26:27], off offset:3072
	s_and_saveexec_b64 s[90:91], s[42:43]
	s_cbranch_execz .LBB0_800
	v_add_co_u32_e32 v18, vcc, 0x1000, v26
	s_nop 1
	v_addc_co_u32_e32 v19, vcc, 0, v27, vcc
	global_load_dwordx4 v[18:21], v[18:19], off

.LBB0_801:
	v_mov_b32_e32 v30, 0
	v_add_u32_e32 v48, v85, v67
	s_movk_i32 s22, 0xfee0
	v_mov_b32_e32 v31, v30
	v_mov_b32_e32 v32, v30
	v_mov_b32_e32 v33, v30
	v_mov_b32_e32 v26, v30
	v_mov_b32_e32 v27, v30
	v_mov_b32_e32 v28, v30
	v_mov_b32_e32 v29, v30
	v_mov_b32_e32 v38, v30
	v_mov_b32_e32 v39, v30
	v_mov_b32_e32 v40, v30
	v_mov_b32_e32 v41, v30
	v_mov_b32_e32 v34, v30
	v_mov_b32_e32 v35, v30
	v_mov_b32_e32 v36, v30
	v_mov_b32_e32 v37, v30
	v_add_lshl_u32 v158, v84, s22, 1
	v_and_b32_e32 v158, -4, v158
	v_add_u32_e32 v158, v65, v158
	v_add_u32_e32 v158, 0xa000, v158
	v_add_u32_e32 v154, 0x260, v158
	v_add_u32_e32 v155, 0x660, v158
	v_add_u32_e32 v156, 0xa60, v158
	v_add_u32_e32 v157, 0xe60, v158
	s_mov_b32 s22, 0
	ds_read2_b32 v[204:205], v157 offset0:128 offset1:129
	ds_read2_b32 v[206:207], v157 offset0:130 offset1:131
	ds_read_b32 v208, v157 offset:528
	ds_read_b128 v[146:149], v48 offset:2048
	ds_read2_b32 v[210:211], v157 offset1:1
	ds_read2_b32 v[212:213], v157 offset0:2 offset1:3
	ds_read_b32 v214, v157 offset:16
	ds_read_b128 v[142:145], v48 offset:1536
	ds_read2_b32 v[216:217], v156 offset0:128 offset1:129
	ds_read2_b32 v[218:219], v156 offset0:130 offset1:131
	ds_read_b32 v220, v156 offset:528
	ds_read_b128 v[138:141], v48 offset:1024
	ds_read2_b32 v[222:223], v156 offset1:1
	ds_read2_b32 v[224:225], v156 offset0:2 offset1:3
	ds_read_b32 v226, v156 offset:16
	ds_read_b128 v[244:247], v48 offset:512
	ds_read2_b32 v[228:229], v155 offset0:128 offset1:129
	ds_read2_b32 v[230:231], v155 offset0:130 offset1:131
	ds_read_b32 v232, v155 offset:528
	ds_read_b128 v[240:243], v48
	ds_read2_b32 v[234:235], v155 offset1:1
	ds_read2_b32 v[236:237], v155 offset0:2 offset1:3
	ds_read_b32 v238, v155 offset:16
	ds_read2_b32 v[126:127], v154 offset0:128 offset1:129
	ds_read2_b32 v[128:129], v154 offset0:130 offset1:131
	ds_read_b32 v130, v154 offset:528
	ds_read2_b32 v[132:133], v154 offset1:1
	ds_read2_b32 v[134:135], v154 offset0:2 offset1:3
	ds_read_b32 v136, v154 offset:16
.Lhl_cv2_b:
	s_waitcnt lgkmcnt(15)
	v_alignbyte_b32 v204, v205, v204, v80
	v_alignbyte_b32 v205, v206, v205, v80
	v_alignbyte_b32 v206, v207, v206, v80
	v_alignbyte_b32 v207, v208, v207, v80
	s_nop 0
	s_nop 0
	v_mfma_f32_16x16x32_bf16 v[34:37], v[204:207], v[146:149], v[34:37]
	ds_read2_b32 v[204:205], v157 offset0:144 offset1:145
	ds_read2_b32 v[206:207], v157 offset0:146 offset1:147
	ds_read_b32 v208, v157 offset:592
	s_waitcnt lgkmcnt(15)
	v_alignbyte_b32 v210, v211, v210, v80
	v_alignbyte_b32 v211, v212, v211, v80
	v_alignbyte_b32 v212, v213, v212, v80
	v_alignbyte_b32 v213, v214, v213, v80
	s_nop 0
	s_nop 0
	v_mfma_f32_16x16x32_bf16 v[38:41], v[210:213], v[146:149], v[38:41]
	v_mfma_f32_16x16x32_bf16 v[34:37], v[210:213], v[142:145], v[34:37]
	ds_read2_b32 v[210:211], v157 offset0:16 offset1:17
	ds_read2_b32 v[212:213], v157 offset0:18 offset1:19
	ds_read_b32 v214, v157 offset:80
	s_waitcnt lgkmcnt(14)
	v_alignbyte_b32 v216, v217, v216, v80
	v_alignbyte_b32 v217, v218, v217, v80
	v_alignbyte_b32 v218, v219, v218, v80
	v_alignbyte_b32 v219, v220, v219, v80
	s_nop 0
	s_nop 0
	v_mfma_f32_16x16x32_bf16 v[26:29], v[216:219], v[146:149], v[26:29]
	v_mfma_f32_16x16x32_bf16 v[38:41], v[216:219], v[142:145], v[38:41]
	v_mfma_f32_16x16x32_bf16 v[34:37], v[216:219], v[138:141], v[34:37]
	ds_read2_b32 v[216:217], v156 offset0:144 offset1:145
	ds_read2_b32 v[218:219], v156 offset0:146 offset1:147
	ds_read_b32 v220, v156 offset:592
	s_waitcnt lgkmcnt(13)
	v_alignbyte_b32 v222, v223, v222, v80
	v_alignbyte_b32 v223, v224, v223, v80
	v_alignbyte_b32 v224, v225, v224, v80
	v_alignbyte_b32 v225, v226, v225, v80
	s_nop 0
	s_nop 0
	v_mfma_f32_16x16x32_bf16 v[30:33], v[222:225], v[146:149], v[30:33]
	v_mfma_f32_16x16x32_bf16 v[26:29], v[222:225], v[142:145], v[26:29]
	v_mfma_f32_16x16x32_bf16 v[38:41], v[222:225], v[138:141], v[38:41]
	v_mfma_f32_16x16x32_bf16 v[34:37], v[222:225], v[244:247], v[34:37]
	ds_read2_b32 v[222:223], v156 offset0:16 offset1:17
	ds_read2_b32 v[224:225], v156 offset0:18 offset1:19
	ds_read_b32 v226, v156 offset:80
	ds_read_b128 v[146:149], v48 offset:2112
	s_waitcnt lgkmcnt(13)
	v_alignbyte_b32 v228, v229, v228, v80
	v_alignbyte_b32 v229, v230, v229, v80
	v_alignbyte_b32 v230, v231, v230, v80
	v_alignbyte_b32 v231, v232, v231, v80
	s_nop 0
	s_nop 0
	v_mfma_f32_16x16x32_bf16 v[30:33], v[228:231], v[142:145], v[30:33]
	v_mfma_f32_16x16x32_bf16 v[26:29], v[228:231], v[138:141], v[26:29]
	v_mfma_f32_16x16x32_bf16 v[38:41], v[228:231], v[244:247], v[38:41]
	v_mfma_f32_16x16x32_bf16 v[34:37], v[228:231], v[240:243], v[34:37]
	ds_read2_b32 v[228:229], v155 offset0:144 offset1:145
	ds_read2_b32 v[230:231], v155 offset0:146 offset1:147
	ds_read_b32 v232, v155 offset:592
	ds_read_b128 v[142:145], v48 offset:1600
	s_waitcnt lgkmcnt(15)
	v_alignbyte_b32 v234, v235, v234, v80
	v_alignbyte_b32 v235, v236, v235, v80
	v_alignbyte_b32 v236, v237, v236, v80
	v_alignbyte_b32 v237, v238, v237, v80
	s_nop 0
	s_nop 0
	v_mfma_f32_16x16x32_bf16 v[30:33], v[234:237], v[138:141], v[30:33]
	v_mfma_f32_16x16x32_bf16 v[26:29], v[234:237], v[244:247], v[26:29]
	v_mfma_f32_16x16x32_bf16 v[38:41], v[234:237], v[240:243], v[38:41]
	ds_read2_b32 v[234:235], v155 offset0:16 offset1:17
	ds_read2_b32 v[236:237], v155 offset0:18 offset1:19
	ds_read_b32 v238, v155 offset:80
	ds_read_b128 v[138:141], v48 offset:1088
	s_waitcnt lgkmcnt(15)
	v_alignbyte_b32 v126, v127, v126, v80
	v_alignbyte_b32 v127, v128, v127, v80
	v_alignbyte_b32 v128, v129, v128, v80
	v_alignbyte_b32 v129, v130, v129, v80
	s_nop 0
	s_nop 0
	v_mfma_f32_16x16x32_bf16 v[30:33], v[126:129], v[244:247], v[30:33]
	v_mfma_f32_16x16x32_bf16 v[26:29], v[126:129], v[240:243], v[26:29]
	ds_read2_b32 v[126:127], v154 offset0:144 offset1:145
	ds_read2_b32 v[128:129], v154 offset0:146 offset1:147
	ds_read_b32 v130, v154 offset:592
	ds_read_b128 v[244:247], v48 offset:576
	s_waitcnt lgkmcnt(15)
	v_alignbyte_b32 v132, v133, v132, v80
	v_alignbyte_b32 v133, v134, v133, v80
	v_alignbyte_b32 v134, v135, v134, v80
	v_alignbyte_b32 v135, v136, v135, v80
	s_nop 0
	s_nop 0
	v_mfma_f32_16x16x32_bf16 v[30:33], v[132:135], v[240:243], v[30:33]
	ds_read2_b32 v[132:133], v154 offset0:16 offset1:17
	ds_read2_b32 v[134:135], v154 offset0:18 offset1:19
	ds_read_b32 v136, v154 offset:80
	ds_read_b128 v[240:243], v48 offset:64
	v_add_u32_e32 v48, 64, v48
	v_add_u32_e32 v154, 64, v154
	v_add_u32_e32 v155, 64, v155
	v_add_u32_e32 v156, 64, v156
	v_add_u32_e32 v157, 64, v157
	s_add_i32 s22, s22, 1
	s_cmp_lt_i32 s22, 8
	s_cbranch_scc1 .Lhl_cv2_b
	s_waitcnt lgkmcnt(0)
	v_add_f32_e32 v42, v46, v47
	v_div_scale_f32 v43, s[22:23], v42, v42, 1.0
	v_rcp_f32_e32 v44, v43
	s_mov_b32 s22, 4
	s_mov_b64 s[90:91], 0
	s_mov_b64 s[92:93], -1
	v_fma_f32 v45, -v43, v44, 1.0
	v_fmac_f32_e32 v44, v45, v44
	v_div_scale_f32 v45, vcc, 1.0, v42, 1.0
	v_mul_f32_e32 v46, v45, v44
	v_fma_f32 v47, -v43, v46, v45
	v_fmac_f32_e32 v46, v47, v44
	v_fma_f32 v43, -v43, v46, v45
	v_div_fmas_f32 v43, v43, v44, v46
	ds_read2st64_b64 v[44:47], v59 offset0:1 offset1:2
	v_div_fixup_f32 v42, v43, v42, 1.0
	s_and_b64 vcc, exec, s[88:89]
	s_waitcnt lgkmcnt(0)
	v_and_b32_e32 v49, 0xffff0000, v44
	v_lshlrev_b32_e32 v48, 16, v44
	s_waitcnt vmcnt(0)
	v_pk_mul_f32 v[48:49], v[64:65], v[48:49] op_sel_hi:[0,1]
	v_pk_fma_f32 v[34:35], v[42:43], v[34:35], v[48:49] op_sel_hi:[0,1,1]
	v_and_b32_e32 v49, 0xffff0000, v45
	v_lshlrev_b32_e32 v48, 16, v45
	v_pk_mul_f32 v[44:45], v[64:65], v[48:49] op_sel_hi:[0,1]
	v_pk_fma_f32 v[36:37], v[42:43], v[36:37], v[44:45] op_sel_hi:[0,1,1]
	v_bfe_u32 v43, v37, 16, 1
	v_bfe_u32 v44, v36, 16, 1
	v_bfe_u32 v45, v35, 16, 1
	v_add3_u32 v45, v35, v45, s94
	v_add3_u32 v35, v36, v44, s94
	v_add3_u32 v36, v37, v43, s94
	v_perm_b32 v35, v36, v35, s95
	v_and_b32_e32 v37, 0xffff0000, v46
	v_lshlrev_b32_e32 v36, 16, v46
	v_pk_mul_f32 v[36:37], v[64:65], v[36:37] op_sel_hi:[0,1]
	v_pk_fma_f32 v[36:37], v[42:43], v[38:39], v[36:37] op_sel_hi:[0,1,1]
	v_and_b32_e32 v39, 0xffff0000, v47
	v_lshlrev_b32_e32 v38, 16, v47
	v_pk_mul_f32 v[38:39], v[64:65], v[38:39] op_sel_hi:[0,1]
	v_pk_fma_f32 v[38:39], v[42:43], v[40:41], v[38:39] op_sel_hi:[0,1,1]
	v_bfe_u32 v48, v34, 16, 1
	v_bfe_u32 v43, v37, 16, 1
	v_bfe_u32 v44, v36, 16, 1
	v_add3_u32 v34, v34, v48, s94
	v_add3_u32 v36, v36, v44, s94
	v_add3_u32 v43, v37, v43, s94
	v_cvt_pk_bf16_f32 v38, v38, v39
	v_perm_b32 v34, v45, v34, s95
	v_mov_b32_e32 v37, v38
	v_perm_b32 v36, v43, v36, s95
	ds_write2st64_b64 v59, v[34:35], v[36:37] offset0:1 offset1:2
	ds_read2st64_b64 v[34:37], v59 offset0:3 offset1:4
	s_waitcnt lgkmcnt(0)
	v_and_b32_e32 v39, 0xffff0000, v34
	v_lshlrev_b32_e32 v38, 16, v34
	v_pk_mul_f32 v[38:39], v[64:65], v[38:39] op_sel_hi:[0,1]
	v_pk_fma_f32 v[26:27], v[42:43], v[26:27], v[38:39] op_sel_hi:[0,1,1]
	v_and_b32_e32 v39, 0xffff0000, v35
	v_lshlrev_b32_e32 v38, 16, v35
	v_pk_mul_f32 v[34:35], v[64:65], v[38:39] op_sel_hi:[0,1]
	v_pk_fma_f32 v[28:29], v[42:43], v[28:29], v[34:35] op_sel_hi:[0,1,1]
	v_bfe_u32 v38, v27, 16, 1
	v_add3_u32 v38, v27, v38, s94
	v_cvt_pk_bf16_f32 v28, v28, v29
	v_mov_b32_e32 v27, v28
	v_and_b32_e32 v29, 0xffff0000, v36
	v_lshlrev_b32_e32 v28, 16, v36
	v_pk_mul_f32 v[28:29], v[64:65], v[28:29] op_sel_hi:[0,1]
	v_pk_fma_f32 v[28:29], v[42:43], v[30:31], v[28:29] op_sel_hi:[0,1,1]
	v_and_b32_e32 v31, 0xffff0000, v37
	v_lshlrev_b32_e32 v30, 16, v37
	v_pk_mul_f32 v[30:31], v[64:65], v[30:31] op_sel_hi:[0,1]
	v_pk_fma_f32 v[30:31], v[42:43], v[32:33], v[30:31] op_sel_hi:[0,1,1]
	v_bfe_u32 v39, v26, 16, 1
	v_bfe_u32 v34, v29, 16, 1
	v_bfe_u32 v35, v28, 16, 1
	v_add3_u32 v26, v26, v39, s94
	v_add3_u32 v28, v28, v35, s94
	v_add3_u32 v34, v29, v34, s94
	v_cvt_pk_bf16_f32 v30, v30, v31
	v_perm_b32 v26, v38, v26, s95
	v_mov_b32_e32 v29, v30
	v_perm_b32 v28, v34, v28, s95
	ds_write2st64_b64 v59, v[26:27], v[28:29] offset0:3 offset1:4
	s_cbranch_vccz .LBB0_789
	v_cmp_eq_u32_e32 vcc, 0, v0
	s_and_saveexec_b64 s[42:43], vcc
	s_cbranch_execz .LBB0_838
	s_lshr_b32 s20, s20, 3
	s_and_b32 s20, s20, 4
	v_readlane_b32 s22, v251, 49
	s_add_u32 s20, s22, s20
	v_readlane_b32 s22, v251, 50
	s_addc_u32 s22, s22, 0
	s_lshl_b32 s21, s21, 5
	s_add_u32 s88, s20, s21
	s_addc_u32 s89, s22, 0
	s_mov_b32 s20, 0x400001
	s_branch .LBB0_807
